# up-projection epilogue: the eight row sum-of-squares loads issued together at the top (all original memory waits kept)
# baseline (speedup 1.0000x reference)
; __device__ __forceinline__ u32x4 pack8(const f32x4 a, const f32x4 b) { u32x4 w; w.x = cvt_pk_bf16(a[0], a[1]); w.y = cvt_pk_bf16(a[2], a[3]); w.z = cvt_pk_bf16(b[0], b[1]); w.w = cvt_pk_bf16(b[2], b[3]); return w; }
;     __device__ __forceinline__ void operator()(const f32x4 (&acc)[2][2][4][2], const Unit& u, int wr, int wc, int fr, int fq) const {
;     ...
;         for (int ai = 0; ai < 2; ++ai)
; #pragma unroll
;             for (int m = 0; m < 4; ++m) {
;                 const int row = u.pm * BM + ai * HALF + wr * 64 + m * 16 + fr;
;                 const float rstd = rsqrtf(ssq[row] * (1.0f / 2048.0f) + EPS);
; #pragma unroll
;                 for (int bj = 0; bj < 2; ++bj) {
;                     const int col = u.pn * BM + bj * HALF + wc * 32 + 8 * fq;
;                     f32x4 v0 = acc[ai][bj][m][0] * rstd, v1 = acc[ai][bj][m][1] * rstd;
; #pragma unroll
;                     for (int k = 0; k < 4; ++k) { const float a = fmaxf(v0[k], 0.f), b = fmaxf(v1[k], 0.f); v0[k] = a * a; v1[k] = b * b; }
;                     *(u32x4*)(HID + (size_t)row * 8192 + col) = pack8(v0, v1);
.LBB0_731:
	s_lshl_b32 s17, s24, 8
	v_mov_b32_e32 v144, v148
	v_mov_b32_e32 v155, v149
	s_add_i32 s17, s17, s38
	s_nop 0
	v_add_u32_e32 v146, s17, v144
	v_ashrrev_i32_e32 v147, 31, v146
	v_lshl_add_u64 v[144:145], v[146:147], 2, s[94:95]
	v_lshlrev_b32_e32 v248, 2, v146
	global_load_dword v240, v248, s[94:95]
	global_load_dword v241, v248, s[94:95] offset:64
	global_load_dword v242, v248, s[94:95] offset:128
	global_load_dword v243, v248, s[94:95] offset:192
	global_load_dword v244, v248, s[94:95] offset:512
	global_load_dword v245, v248, s[94:95] offset:576
	global_load_dword v246, v248, s[94:95] offset:640
	global_load_dword v247, v248, s[94:95] offset:704
	s_lshl_b32 s17, s46, 8
	s_or_b32 s17, s17, s39
	v_lshlrev_b64 v[158:159], 14, v[146:147]
	v_lshl_add_u32 v144, v155, 3, s17
	v_ashrrev_i32_e32 v145, 31, v144
	v_add_u32_e32 v156, 16, v146
	v_lshlrev_b64 v[144:145], 1, v[144:145]
	v_lshl_add_u64 v[158:159], s[80:81], 0, v[158:159]
	v_ashrrev_i32_e32 v157, 31, v156
	v_lshl_add_u64 v[158:159], v[158:159], 0, v[144:145]
	s_waitcnt vmcnt(0)
	v_fmamk_f32 v147, v240, 0x3a000000, v154
	v_mul_f32_e32 v155, 0x4b800000, v147
	v_cmp_gt_f32_e32 vcc, s45, v147
	v_lshl_add_u64 v[160:161], v[156:157], 2, s[94:95]
	s_nop 0
	v_cndmask_b32_e32 v147, v147, v155, vcc
	v_rsq_f32_e32 v147, v147
	s_nop 0
	v_mul_f32_e32 v155, 0x45800000, v147
	v_cndmask_b32_e32 v162, v147, v155, vcc
	v_pk_mul_f32 v[126:127], v[126:127], v[162:163] op_sel_hi:[1,0]
	v_pk_mul_f32 v[124:125], v[124:125], v[162:163] op_sel_hi:[1,0]
	v_pk_mul_f32 v[122:123], v[122:123], v[162:163] op_sel_hi:[1,0]
	v_pk_mul_f32 v[120:121], v[120:121], v[162:163] op_sel_hi:[1,0]
	v_pk_mul_f32 v[114:115], v[114:115], v[162:163] op_sel_hi:[1,0]
	v_pk_mul_f32 v[112:113], v[112:113], v[162:163] op_sel_hi:[1,0]
	v_pk_mul_f32 v[118:119], v[118:119], v[162:163] op_sel_hi:[1,0]
	v_pk_mul_f32 v[116:117], v[116:117], v[162:163] op_sel_hi:[1,0]
	v_max_f32_e32 v124, 0, v124
	v_max_f32_e32 v120, 0, v120
	v_max_f32_e32 v125, 0, v125
	v_max_f32_e32 v121, 0, v121
	v_max_f32_e32 v126, 0, v126
	v_max_f32_e32 v122, 0, v122
	v_max_f32_e32 v127, 0, v127
	v_max_f32_e32 v123, 0, v123
	v_max_f32_e32 v112, 0, v112
	v_max_f32_e32 v113, 0, v113
	v_max_f32_e32 v114, 0, v114
	v_max_f32_e32 v115, 0, v115
	v_max_f32_e32 v116, 0, v116
	v_max_f32_e32 v117, 0, v117
	v_max_f32_e32 v118, 0, v118
	v_max_f32_e32 v119, 0, v119
	v_mul_f32_e32 v124, v124, v124
	v_mul_f32_e32 v120, v120, v120
	v_mul_f32_e32 v125, v125, v125
	v_mul_f32_e32 v121, v121, v121
	v_mul_f32_e32 v126, v126, v126
	v_mul_f32_e32 v122, v122, v122
	v_mul_f32_e32 v127, v127, v127
	v_mul_f32_e32 v123, v123, v123
	v_mul_f32_e32 v147, v112, v112
	v_mul_f32_e32 v155, v113, v113
	v_mul_f32_e32 v162, v114, v114
	v_mul_f32_e32 v163, v115, v115
	v_cvt_pk_bf16_f32 v112, v124, v125
	v_cvt_pk_bf16_f32 v113, v126, v127
	v_cvt_pk_bf16_f32 v114, v120, v121
	v_cvt_pk_bf16_f32 v115, v122, v123
	v_mul_f32_e32 v116, v116, v116
	v_mul_f32_e32 v117, v117, v117
	v_mul_f32_e32 v118, v118, v118
	v_mul_f32_e32 v119, v119, v119
	global_store_dwordx4 v[158:159], v[112:115], off
	s_nop 1
	v_cvt_pk_bf16_f32 v112, v116, v117
	v_cvt_pk_bf16_f32 v113, v118, v119
	v_cvt_pk_bf16_f32 v114, v147, v155
	v_cvt_pk_bf16_f32 v115, v162, v163
	global_store_dwordx4 v[158:159], v[112:115], off offset:256
	s_waitcnt vmcnt(0)
	v_fmamk_f32 v116, v241, 0x3a000000, v154
	v_mul_f32_e32 v117, 0x4b800000, v116
	v_cmp_gt_f32_e32 vcc, s45, v116
	v_lshlrev_b64 v[114:115], 14, v[156:157]
	v_add_u32_e32 v112, 32, v146
	v_cndmask_b32_e32 v116, v116, v117, vcc
	v_rsq_f32_e32 v118, v116
	v_lshl_add_u64 v[114:115], s[80:81], 0, v[114:115]
	v_ashrrev_i32_e32 v113, 31, v112
	v_lshl_add_u64 v[114:115], v[114:115], 0, v[144:145]
	v_mul_f32_e32 v119, 0x45800000, v118
	v_cndmask_b32_e32 v118, v118, v119, vcc
	v_pk_mul_f32 v[110:111], v[110:111], v[118:119] op_sel_hi:[1,0]
	v_pk_mul_f32 v[108:109], v[108:109], v[118:119] op_sel_hi:[1,0]
	v_pk_mul_f32 v[106:107], v[106:107], v[118:119] op_sel_hi:[1,0]
	v_pk_mul_f32 v[104:105], v[104:105], v[118:119] op_sel_hi:[1,0]
	v_pk_mul_f32 v[98:99], v[98:99], v[118:119] op_sel_hi:[1,0]
	v_pk_mul_f32 v[96:97], v[96:97], v[118:119] op_sel_hi:[1,0]
	v_pk_mul_f32 v[102:103], v[102:103], v[118:119] op_sel_hi:[1,0]
	v_pk_mul_f32 v[100:101], v[100:101], v[118:119] op_sel_hi:[1,0]
	v_max_f32_e32 v108, 0, v108
	v_max_f32_e32 v104, 0, v104
	v_max_f32_e32 v109, 0, v109
	v_max_f32_e32 v105, 0, v105
	v_max_f32_e32 v110, 0, v110
	v_max_f32_e32 v106, 0, v106
	v_max_f32_e32 v111, 0, v111
	v_max_f32_e32 v107, 0, v107
	v_max_f32_e32 v96, 0, v96
	v_max_f32_e32 v97, 0, v97
	v_max_f32_e32 v98, 0, v98
	v_max_f32_e32 v99, 0, v99
	v_max_f32_e32 v100, 0, v100
	v_max_f32_e32 v101, 0, v101
	v_max_f32_e32 v102, 0, v102
	v_max_f32_e32 v103, 0, v103
	v_mul_f32_e32 v108, v108, v108
	v_mul_f32_e32 v104, v104, v104
	v_mul_f32_e32 v109, v109, v109
	v_mul_f32_e32 v105, v105, v105
	v_mul_f32_e32 v110, v110, v110
	v_mul_f32_e32 v106, v106, v106
	v_mul_f32_e32 v111, v111, v111
	v_mul_f32_e32 v107, v107, v107
	v_mul_f32_e32 v118, v96, v96
	v_mul_f32_e32 v119, v97, v97
	v_mul_f32_e32 v120, v98, v98
	v_mul_f32_e32 v121, v99, v99
	v_cvt_pk_bf16_f32 v96, v108, v109
	v_cvt_pk_bf16_f32 v97, v110, v111
	v_cvt_pk_bf16_f32 v98, v104, v105
	v_cvt_pk_bf16_f32 v99, v106, v107
	v_lshl_add_u64 v[116:117], v[112:113], 2, s[94:95]
	v_mul_f32_e32 v100, v100, v100
	v_mul_f32_e32 v101, v101, v101
	v_mul_f32_e32 v102, v102, v102
	v_mul_f32_e32 v103, v103, v103
	global_store_dwordx4 v[114:115], v[96:99], off
	s_nop 1
	v_cvt_pk_bf16_f32 v96, v100, v101
	v_cvt_pk_bf16_f32 v97, v102, v103
	v_cvt_pk_bf16_f32 v98, v118, v119
	v_cvt_pk_bf16_f32 v99, v120, v121
	global_store_dwordx4 v[114:115], v[96:99], off offset:256
	s_waitcnt vmcnt(0)
; __device__ __forceinline__ u32x4 pack8(const f32x4 a, const f32x4 b) { u32x4 w; w.x = cvt_pk_bf16(a[0], a[1]); w.y = cvt_pk_bf16(a[2], a[3]); w.z = cvt_pk_bf16(b[0], b[1]); w.w = cvt_pk_bf16(b[2], b[3]); return w; }
;     __device__ __forceinline__ void operator()(const f32x4 (&acc)[2][2][4][2], const Unit& u, int wr, int wc, int fr, int fq) const {
;     ...
;         for (int ai = 0; ai < 2; ++ai)
; #pragma unroll
;             for (int m = 0; m < 4; ++m) {
;                 const int row = u.pm * BM + ai * HALF + wr * 64 + m * 16 + fr;
;                 const float rstd = rsqrtf(ssq[row] * (1.0f / 2048.0f) + EPS);
; #pragma unroll
;                 for (int bj = 0; bj < 2; ++bj) {
;                     const int col = u.pn * BM + bj * HALF + wc * 32 + 8 * fq;
;                     f32x4 v0 = acc[ai][bj][m][0] * rstd, v1 = acc[ai][bj][m][1] * rstd;
; #pragma unroll
;                     for (int k = 0; k < 4; ++k) { const float a = fmaxf(v0[k], 0.f), b = fmaxf(v1[k], 0.f); v0[k] = a * a; v1[k] = b * b; }
;                     *(u32x4*)(HID + (size_t)row * 8192 + col) = pack8(v0, v1);
	v_fmamk_f32 v100, v242, 0x3a000000, v154
	v_mul_f32_e32 v101, 0x4b800000, v100
	v_cmp_gt_f32_e32 vcc, s45, v100
	v_lshlrev_b64 v[98:99], 14, v[112:113]
	v_add_u32_e32 v96, 48, v146
	v_cndmask_b32_e32 v100, v100, v101, vcc
	v_rsq_f32_e32 v102, v100
	v_lshl_add_u64 v[98:99], s[80:81], 0, v[98:99]
	v_ashrrev_i32_e32 v97, 31, v96
	v_lshl_add_u64 v[98:99], v[98:99], 0, v[144:145]
	v_mul_f32_e32 v103, 0x45800000, v102
	v_cndmask_b32_e32 v102, v102, v103, vcc
	v_pk_mul_f32 v[94:95], v[94:95], v[102:103] op_sel_hi:[1,0]
	v_pk_mul_f32 v[92:93], v[92:93], v[102:103] op_sel_hi:[1,0]
	v_pk_mul_f32 v[90:91], v[90:91], v[102:103] op_sel_hi:[1,0]
	v_pk_mul_f32 v[88:89], v[88:89], v[102:103] op_sel_hi:[1,0]
	v_pk_mul_f32 v[82:83], v[82:83], v[102:103] op_sel_hi:[1,0]
	v_pk_mul_f32 v[80:81], v[80:81], v[102:103] op_sel_hi:[1,0]
	v_pk_mul_f32 v[86:87], v[86:87], v[102:103] op_sel_hi:[1,0]
	v_pk_mul_f32 v[84:85], v[84:85], v[102:103] op_sel_hi:[1,0]
	v_max_f32_e32 v92, 0, v92
	v_max_f32_e32 v88, 0, v88
	v_max_f32_e32 v93, 0, v93
	v_max_f32_e32 v89, 0, v89
	v_max_f32_e32 v94, 0, v94
	v_max_f32_e32 v90, 0, v90
	v_max_f32_e32 v95, 0, v95
	v_max_f32_e32 v91, 0, v91
	v_max_f32_e32 v80, 0, v80
	v_max_f32_e32 v81, 0, v81
	v_max_f32_e32 v82, 0, v82
	v_max_f32_e32 v83, 0, v83
	v_max_f32_e32 v84, 0, v84
	v_max_f32_e32 v85, 0, v85
	v_max_f32_e32 v86, 0, v86
	v_max_f32_e32 v87, 0, v87
	v_mul_f32_e32 v92, v92, v92
	v_mul_f32_e32 v88, v88, v88
	v_mul_f32_e32 v93, v93, v93
	v_mul_f32_e32 v89, v89, v89
	v_mul_f32_e32 v94, v94, v94
	v_mul_f32_e32 v90, v90, v90
	v_mul_f32_e32 v95, v95, v95
	v_mul_f32_e32 v91, v91, v91
	v_mul_f32_e32 v102, v80, v80
	v_mul_f32_e32 v103, v81, v81
	v_mul_f32_e32 v104, v82, v82
	v_mul_f32_e32 v105, v83, v83
	v_cvt_pk_bf16_f32 v80, v92, v93
	v_cvt_pk_bf16_f32 v81, v94, v95
	v_cvt_pk_bf16_f32 v82, v88, v89
	v_cvt_pk_bf16_f32 v83, v90, v91
	v_lshl_add_u64 v[100:101], v[96:97], 2, s[94:95]
	v_mul_f32_e32 v84, v84, v84
	v_mul_f32_e32 v85, v85, v85
	v_mul_f32_e32 v86, v86, v86
	v_mul_f32_e32 v87, v87, v87
	global_store_dwordx4 v[98:99], v[80:83], off
	s_nop 1
	v_cvt_pk_bf16_f32 v80, v84, v85
	v_cvt_pk_bf16_f32 v81, v86, v87
	v_cvt_pk_bf16_f32 v82, v102, v103
	v_cvt_pk_bf16_f32 v83, v104, v105
	global_store_dwordx4 v[98:99], v[80:83], off offset:256
	s_waitcnt vmcnt(0)
	v_fmamk_f32 v84, v243, 0x3a000000, v154
	v_mul_f32_e32 v85, 0x4b800000, v84
	v_cmp_gt_f32_e32 vcc, s45, v84
	v_lshlrev_b64 v[82:83], 14, v[96:97]
	v_add_u32_e32 v80, 0x80, v146
	v_cndmask_b32_e32 v84, v84, v85, vcc
	v_rsq_f32_e32 v86, v84
	v_lshl_add_u64 v[82:83], s[80:81], 0, v[82:83]
	v_ashrrev_i32_e32 v81, 31, v80
	v_lshl_add_u64 v[82:83], v[82:83], 0, v[144:145]
	v_mul_f32_e32 v87, 0x45800000, v86
	v_cndmask_b32_e32 v86, v86, v87, vcc
	v_pk_mul_f32 v[78:79], v[78:79], v[86:87] op_sel_hi:[1,0]
	v_pk_mul_f32 v[76:77], v[76:77], v[86:87] op_sel_hi:[1,0]
	v_pk_mul_f32 v[74:75], v[74:75], v[86:87] op_sel_hi:[1,0]
	v_pk_mul_f32 v[72:73], v[72:73], v[86:87] op_sel_hi:[1,0]
	v_pk_mul_f32 v[66:67], v[66:67], v[86:87] op_sel_hi:[1,0]
	v_pk_mul_f32 v[64:65], v[64:65], v[86:87] op_sel_hi:[1,0]
	v_pk_mul_f32 v[70:71], v[70:71], v[86:87] op_sel_hi:[1,0]
	v_pk_mul_f32 v[68:69], v[68:69], v[86:87] op_sel_hi:[1,0]
	v_max_f32_e32 v76, 0, v76
	v_max_f32_e32 v72, 0, v72
	v_max_f32_e32 v77, 0, v77
	v_max_f32_e32 v73, 0, v73
	v_max_f32_e32 v78, 0, v78
	v_max_f32_e32 v74, 0, v74
	v_max_f32_e32 v79, 0, v79
	v_max_f32_e32 v75, 0, v75
	v_max_f32_e32 v64, 0, v64
	v_max_f32_e32 v65, 0, v65
	v_max_f32_e32 v66, 0, v66
	v_max_f32_e32 v67, 0, v67
	v_max_f32_e32 v68, 0, v68
	v_max_f32_e32 v69, 0, v69
	v_max_f32_e32 v70, 0, v70
	v_max_f32_e32 v71, 0, v71
	v_mul_f32_e32 v76, v76, v76
	v_mul_f32_e32 v72, v72, v72
	v_mul_f32_e32 v77, v77, v77
	v_mul_f32_e32 v73, v73, v73
	v_mul_f32_e32 v78, v78, v78
	v_mul_f32_e32 v74, v74, v74
	v_mul_f32_e32 v79, v79, v79
	v_mul_f32_e32 v75, v75, v75
	v_mul_f32_e32 v86, v64, v64
	v_mul_f32_e32 v87, v65, v65
	v_mul_f32_e32 v88, v66, v66
	v_mul_f32_e32 v89, v67, v67
	v_cvt_pk_bf16_f32 v64, v76, v77
	v_cvt_pk_bf16_f32 v65, v78, v79
	v_cvt_pk_bf16_f32 v66, v72, v73
	v_cvt_pk_bf16_f32 v67, v74, v75
	v_lshl_add_u64 v[84:85], v[80:81], 2, s[94:95]
	v_mul_f32_e32 v68, v68, v68
	v_mul_f32_e32 v69, v69, v69
	v_mul_f32_e32 v70, v70, v70
	v_mul_f32_e32 v71, v71, v71
	global_store_dwordx4 v[82:83], v[64:67], off
	s_nop 1
	v_cvt_pk_bf16_f32 v64, v68, v69
	v_cvt_pk_bf16_f32 v65, v70, v71
	v_cvt_pk_bf16_f32 v66, v86, v87
	v_cvt_pk_bf16_f32 v67, v88, v89
	global_store_dwordx4 v[82:83], v[64:67], off offset:256
	s_waitcnt vmcnt(0)
; __device__ __forceinline__ u32x4 pack8(const f32x4 a, const f32x4 b) { u32x4 w; w.x = cvt_pk_bf16(a[0], a[1]); w.y = cvt_pk_bf16(a[2], a[3]); w.z = cvt_pk_bf16(b[0], b[1]); w.w = cvt_pk_bf16(b[2], b[3]); return w; }
;     __device__ __forceinline__ void operator()(const f32x4 (&acc)[2][2][4][2], const Unit& u, int wr, int wc, int fr, int fq) const {
;     ...
;         for (int ai = 0; ai < 2; ++ai)
; #pragma unroll
;             for (int m = 0; m < 4; ++m) {
;                 const int row = u.pm * BM + ai * HALF + wr * 64 + m * 16 + fr;
;                 const float rstd = rsqrtf(ssq[row] * (1.0f / 2048.0f) + EPS);
; #pragma unroll
;                 for (int bj = 0; bj < 2; ++bj) {
;                     const int col = u.pn * BM + bj * HALF + wc * 32 + 8 * fq;
;                     f32x4 v0 = acc[ai][bj][m][0] * rstd, v1 = acc[ai][bj][m][1] * rstd;
; #pragma unroll
;                     for (int k = 0; k < 4; ++k) { const float a = fmaxf(v0[k], 0.f), b = fmaxf(v1[k], 0.f); v0[k] = a * a; v1[k] = b * b; }
;                     *(u32x4*)(HID + (size_t)row * 8192 + col) = pack8(v0, v1);
	v_fmamk_f32 v68, v244, 0x3a000000, v154
	v_mul_f32_e32 v69, 0x4b800000, v68
	v_cmp_gt_f32_e32 vcc, s45, v68
	v_lshlrev_b64 v[66:67], 14, v[80:81]
	v_add_u32_e32 v64, 0x90, v146
	v_cndmask_b32_e32 v68, v68, v69, vcc
	v_rsq_f32_e32 v70, v68
	v_lshl_add_u64 v[66:67], s[80:81], 0, v[66:67]
	v_ashrrev_i32_e32 v65, 31, v64
	v_lshl_add_u64 v[66:67], v[66:67], 0, v[144:145]
	v_mul_f32_e32 v71, 0x45800000, v70
	v_cndmask_b32_e32 v70, v70, v71, vcc
	v_pk_mul_f32 v[62:63], v[62:63], v[70:71] op_sel_hi:[1,0]
	v_pk_mul_f32 v[60:61], v[60:61], v[70:71] op_sel_hi:[1,0]
	v_pk_mul_f32 v[58:59], v[58:59], v[70:71] op_sel_hi:[1,0]
	v_pk_mul_f32 v[56:57], v[56:57], v[70:71] op_sel_hi:[1,0]
	v_pk_mul_f32 v[50:51], v[50:51], v[70:71] op_sel_hi:[1,0]
	v_pk_mul_f32 v[48:49], v[48:49], v[70:71] op_sel_hi:[1,0]
	v_pk_mul_f32 v[54:55], v[54:55], v[70:71] op_sel_hi:[1,0]
	v_pk_mul_f32 v[52:53], v[52:53], v[70:71] op_sel_hi:[1,0]
	v_max_f32_e32 v60, 0, v60
	v_max_f32_e32 v56, 0, v56
	v_max_f32_e32 v61, 0, v61
	v_max_f32_e32 v57, 0, v57
	v_max_f32_e32 v62, 0, v62
	v_max_f32_e32 v58, 0, v58
	v_max_f32_e32 v63, 0, v63
	v_max_f32_e32 v59, 0, v59
	v_max_f32_e32 v48, 0, v48
	v_max_f32_e32 v49, 0, v49
	v_max_f32_e32 v50, 0, v50
	v_max_f32_e32 v51, 0, v51
	v_max_f32_e32 v52, 0, v52
	v_max_f32_e32 v53, 0, v53
	v_max_f32_e32 v54, 0, v54
	v_max_f32_e32 v55, 0, v55
	v_mul_f32_e32 v60, v60, v60
	v_mul_f32_e32 v56, v56, v56
	v_mul_f32_e32 v61, v61, v61
	v_mul_f32_e32 v57, v57, v57
	v_mul_f32_e32 v62, v62, v62
	v_mul_f32_e32 v58, v58, v58
	v_mul_f32_e32 v63, v63, v63
	v_mul_f32_e32 v59, v59, v59
	v_mul_f32_e32 v70, v48, v48
	v_mul_f32_e32 v71, v49, v49
	v_mul_f32_e32 v72, v50, v50
	v_mul_f32_e32 v73, v51, v51
	v_cvt_pk_bf16_f32 v48, v60, v61
	v_cvt_pk_bf16_f32 v49, v62, v63
	v_cvt_pk_bf16_f32 v50, v56, v57
	v_cvt_pk_bf16_f32 v51, v58, v59
	v_lshl_add_u64 v[68:69], v[64:65], 2, s[94:95]
	v_mul_f32_e32 v52, v52, v52
	v_mul_f32_e32 v53, v53, v53
	v_mul_f32_e32 v54, v54, v54
	v_mul_f32_e32 v55, v55, v55
	global_store_dwordx4 v[66:67], v[48:51], off
	s_nop 1
	v_cvt_pk_bf16_f32 v48, v52, v53
	v_cvt_pk_bf16_f32 v49, v54, v55
	v_cvt_pk_bf16_f32 v50, v70, v71
	v_cvt_pk_bf16_f32 v51, v72, v73
	global_store_dwordx4 v[66:67], v[48:51], off offset:256
	s_waitcnt vmcnt(0)
	v_fmamk_f32 v52, v245, 0x3a000000, v154
	v_mul_f32_e32 v53, 0x4b800000, v52
	v_cmp_gt_f32_e32 vcc, s45, v52
	v_lshlrev_b64 v[50:51], 14, v[64:65]
	v_add_u32_e32 v48, 0xa0, v146
	v_cndmask_b32_e32 v52, v52, v53, vcc
	v_rsq_f32_e32 v54, v52
	v_lshl_add_u64 v[50:51], s[80:81], 0, v[50:51]
	v_ashrrev_i32_e32 v49, 31, v48
	v_lshl_add_u64 v[50:51], v[50:51], 0, v[144:145]
	v_mul_f32_e32 v55, 0x45800000, v54
	v_cndmask_b32_e32 v54, v54, v55, vcc
	v_pk_mul_f32 v[46:47], v[46:47], v[54:55] op_sel_hi:[1,0]
	v_pk_mul_f32 v[44:45], v[44:45], v[54:55] op_sel_hi:[1,0]
	v_pk_mul_f32 v[42:43], v[42:43], v[54:55] op_sel_hi:[1,0]
	v_pk_mul_f32 v[40:41], v[40:41], v[54:55] op_sel_hi:[1,0]
	v_pk_mul_f32 v[34:35], v[34:35], v[54:55] op_sel_hi:[1,0]
	v_pk_mul_f32 v[32:33], v[32:33], v[54:55] op_sel_hi:[1,0]
	v_pk_mul_f32 v[38:39], v[38:39], v[54:55] op_sel_hi:[1,0]
	v_pk_mul_f32 v[36:37], v[36:37], v[54:55] op_sel_hi:[1,0]
	v_max_f32_e32 v44, 0, v44
	v_max_f32_e32 v40, 0, v40
	v_max_f32_e32 v45, 0, v45
	v_max_f32_e32 v41, 0, v41
	v_max_f32_e32 v46, 0, v46
	v_max_f32_e32 v42, 0, v42
	v_max_f32_e32 v47, 0, v47
	v_max_f32_e32 v43, 0, v43
	v_max_f32_e32 v32, 0, v32
	v_max_f32_e32 v33, 0, v33
	v_max_f32_e32 v34, 0, v34
	v_max_f32_e32 v35, 0, v35
	v_max_f32_e32 v36, 0, v36
	v_max_f32_e32 v37, 0, v37
	v_max_f32_e32 v38, 0, v38
	v_max_f32_e32 v39, 0, v39
	v_mul_f32_e32 v44, v44, v44
	v_mul_f32_e32 v40, v40, v40
	v_mul_f32_e32 v45, v45, v45
	v_mul_f32_e32 v41, v41, v41
	v_mul_f32_e32 v46, v46, v46
	v_mul_f32_e32 v42, v42, v42
	v_mul_f32_e32 v47, v47, v47
	v_mul_f32_e32 v43, v43, v43
	v_mul_f32_e32 v54, v32, v32
	v_mul_f32_e32 v55, v33, v33
	v_mul_f32_e32 v56, v34, v34
	v_mul_f32_e32 v57, v35, v35
	v_cvt_pk_bf16_f32 v32, v44, v45
	v_cvt_pk_bf16_f32 v33, v46, v47
	v_cvt_pk_bf16_f32 v34, v40, v41
	v_cvt_pk_bf16_f32 v35, v42, v43
	v_lshl_add_u64 v[52:53], v[48:49], 2, s[94:95]
	v_mul_f32_e32 v36, v36, v36
	v_mul_f32_e32 v37, v37, v37
	v_mul_f32_e32 v38, v38, v38
	v_mul_f32_e32 v39, v39, v39
	global_store_dwordx4 v[50:51], v[32:35], off
	s_nop 1
	v_cvt_pk_bf16_f32 v32, v36, v37
	v_cvt_pk_bf16_f32 v33, v38, v39
	v_cvt_pk_bf16_f32 v34, v54, v55
	v_cvt_pk_bf16_f32 v35, v56, v57
	global_store_dwordx4 v[50:51], v[32:35], off offset:256
	s_waitcnt vmcnt(0)
; __device__ __forceinline__ u32x4 pack8(const f32x4 a, const f32x4 b) { u32x4 w; w.x = cvt_pk_bf16(a[0], a[1]); w.y = cvt_pk_bf16(a[2], a[3]); w.z = cvt_pk_bf16(b[0], b[1]); w.w = cvt_pk_bf16(b[2], b[3]); return w; }
; #define PG8_BAR __builtin_amdgcn_s_barrier()
; template <class Epi, class Sched, bool ALIGN_EPI = false, bool SP2 = false>
; __device__ __forceinline__ void gemm_phase(PG8_LAS unsigned char* lds, const Gemm g, const Sched& S, const Epi& E) {
;     ...
;         if (!has_next) break;
; #pragma unroll
;         for (int a = 0; a < 2; ++a)
; #pragma unroll
;             for (int b = 0; b < 2; ++b)
; #pragma unroll
;                 for (int m = 0; m < 4; ++m)
; #pragma unroll
;                     for (int n = 0; n < 2; ++n) acc[a][b][m][n] = (f32x4){0.f, 0.f, 0.f, 0.f};
;         cur = nxt; cA = nA; cB = nB; ++ui;
;         if constexpr (ALIGN_EPI) { if (wr == 1) PG8_BAR; }
;     __device__ __forceinline__ void operator()(const f32x4 (&acc)[2][2][4][2], const Unit& u, int wr, int wc, int fr, int fq) const {
;     ...
;         for (int ai = 0; ai < 2; ++ai)
; #pragma unroll
;             for (int m = 0; m < 4; ++m) {
;                 const int row = u.pm * BM + ai * HALF + wr * 64 + m * 16 + fr;
;                 const float rstd = rsqrtf(ssq[row] * (1.0f / 2048.0f) + EPS);
; #pragma unroll
;                 for (int bj = 0; bj < 2; ++bj) {
;                     const int col = u.pn * BM + bj * HALF + wc * 32 + 8 * fq;
;                     f32x4 v0 = acc[ai][bj][m][0] * rstd, v1 = acc[ai][bj][m][1] * rstd;
; #pragma unroll
;                     for (int k = 0; k < 4; ++k) { const float a = fmaxf(v0[k], 0.f), b = fmaxf(v1[k], 0.f); v0[k] = a * a; v1[k] = b * b; }
;                     *(u32x4*)(HID + (size_t)row * 8192 + col) = pack8(v0, v1);
	v_fmamk_f32 v36, v246, 0x3a000000, v154
	v_mul_f32_e32 v37, 0x4b800000, v36
	v_cmp_gt_f32_e32 vcc, s45, v36
	v_lshlrev_b64 v[34:35], 14, v[48:49]
	v_add_u32_e32 v32, 0xb0, v146
	v_cndmask_b32_e32 v36, v36, v37, vcc
	v_rsq_f32_e32 v38, v36
	v_lshl_add_u64 v[34:35], s[80:81], 0, v[34:35]
	v_ashrrev_i32_e32 v33, 31, v32
	v_lshl_add_u64 v[34:35], v[34:35], 0, v[144:145]
	v_mul_f32_e32 v39, 0x45800000, v38
	v_cndmask_b32_e32 v38, v38, v39, vcc
	v_pk_mul_f32 v[30:31], v[30:31], v[38:39] op_sel_hi:[1,0]
	v_pk_mul_f32 v[28:29], v[28:29], v[38:39] op_sel_hi:[1,0]
	v_pk_mul_f32 v[26:27], v[26:27], v[38:39] op_sel_hi:[1,0]
	v_pk_mul_f32 v[24:25], v[24:25], v[38:39] op_sel_hi:[1,0]
	v_pk_mul_f32 v[18:19], v[18:19], v[38:39] op_sel_hi:[1,0]
	v_pk_mul_f32 v[16:17], v[16:17], v[38:39] op_sel_hi:[1,0]
	v_pk_mul_f32 v[22:23], v[22:23], v[38:39] op_sel_hi:[1,0]
	v_pk_mul_f32 v[20:21], v[20:21], v[38:39] op_sel_hi:[1,0]
	v_max_f32_e32 v28, 0, v28
	v_max_f32_e32 v24, 0, v24
	v_max_f32_e32 v29, 0, v29
	v_max_f32_e32 v25, 0, v25
	v_max_f32_e32 v30, 0, v30
	v_max_f32_e32 v26, 0, v26
	v_max_f32_e32 v31, 0, v31
	v_max_f32_e32 v27, 0, v27
	v_max_f32_e32 v16, 0, v16
	v_max_f32_e32 v17, 0, v17
	v_max_f32_e32 v18, 0, v18
	v_max_f32_e32 v19, 0, v19
	v_max_f32_e32 v20, 0, v20
	v_max_f32_e32 v21, 0, v21
	v_max_f32_e32 v22, 0, v22
	v_max_f32_e32 v23, 0, v23
	v_mul_f32_e32 v28, v28, v28
	v_mul_f32_e32 v24, v24, v24
	v_mul_f32_e32 v29, v29, v29
	v_mul_f32_e32 v25, v25, v25
	v_mul_f32_e32 v30, v30, v30
	v_mul_f32_e32 v26, v26, v26
	v_mul_f32_e32 v31, v31, v31
	v_mul_f32_e32 v27, v27, v27
	v_mul_f32_e32 v38, v16, v16
	v_mul_f32_e32 v39, v17, v17
	v_mul_f32_e32 v40, v18, v18
	v_mul_f32_e32 v41, v19, v19
	v_cvt_pk_bf16_f32 v16, v28, v29
	v_cvt_pk_bf16_f32 v17, v30, v31
	v_cvt_pk_bf16_f32 v18, v24, v25
	v_cvt_pk_bf16_f32 v19, v26, v27
	v_lshl_add_u64 v[36:37], v[32:33], 2, s[94:95]
	v_mul_f32_e32 v20, v20, v20
	v_mul_f32_e32 v21, v21, v21
	v_mul_f32_e32 v22, v22, v22
	v_mul_f32_e32 v23, v23, v23
	global_store_dwordx4 v[34:35], v[16:19], off
	s_andn2_b64 vcc, exec, s[4:5]
	s_nop 0
	v_cvt_pk_bf16_f32 v16, v20, v21
	v_cvt_pk_bf16_f32 v17, v22, v23
	v_cvt_pk_bf16_f32 v18, v38, v39
	v_cvt_pk_bf16_f32 v19, v40, v41
	global_store_dwordx4 v[34:35], v[16:19], off offset:256
	s_waitcnt vmcnt(0)
	v_fmamk_f32 v16, v247, 0x3a000000, v154
	v_mul_f32_e32 v17, 0x4b800000, v16
	v_cmp_gt_f32_e64 s[4:5], s45, v16
	s_nop 1
	v_cndmask_b32_e64 v16, v16, v17, s[4:5]
	v_rsq_f32_e32 v18, v16
	v_lshlrev_b64 v[16:17], 14, v[32:33]
	v_lshl_add_u64 v[16:17], s[80:81], 0, v[16:17]
	v_lshl_add_u64 v[16:17], v[16:17], 0, v[144:145]
	v_mul_f32_e32 v19, 0x45800000, v18
	v_cndmask_b32_e64 v18, v18, v19, s[4:5]
	v_pk_mul_f32 v[14:15], v[14:15], v[18:19] op_sel_hi:[1,0]
	v_pk_mul_f32 v[12:13], v[12:13], v[18:19] op_sel_hi:[1,0]
	v_pk_mul_f32 v[10:11], v[10:11], v[18:19] op_sel_hi:[1,0]
	v_pk_mul_f32 v[8:9], v[8:9], v[18:19] op_sel_hi:[1,0]
	v_pk_mul_f32 v[2:3], v[2:3], v[18:19] op_sel_hi:[1,0]
	v_pk_mul_f32 v[0:1], v[0:1], v[18:19] op_sel_hi:[1,0]
	v_pk_mul_f32 v[6:7], v[6:7], v[18:19] op_sel_hi:[1,0]
	v_pk_mul_f32 v[4:5], v[4:5], v[18:19] op_sel_hi:[1,0]
	v_max_f32_e32 v12, 0, v12
	v_max_f32_e32 v8, 0, v8
	v_max_f32_e32 v13, 0, v13
	v_max_f32_e32 v9, 0, v9
	v_max_f32_e32 v14, 0, v14
	v_max_f32_e32 v10, 0, v10
	v_max_f32_e32 v15, 0, v15
	v_max_f32_e32 v11, 0, v11
	v_max_f32_e32 v0, 0, v0
	v_max_f32_e32 v1, 0, v1
	v_max_f32_e32 v2, 0, v2
	v_max_f32_e32 v3, 0, v3
	v_max_f32_e32 v4, 0, v4
	v_max_f32_e32 v5, 0, v5
	v_max_f32_e32 v6, 0, v6
	v_max_f32_e32 v7, 0, v7
	v_mul_f32_e32 v12, v12, v12
	v_mul_f32_e32 v8, v8, v8
	v_mul_f32_e32 v13, v13, v13
	v_mul_f32_e32 v9, v9, v9
	v_mul_f32_e32 v14, v14, v14
	v_mul_f32_e32 v10, v10, v10
	v_mul_f32_e32 v15, v15, v15
	v_mul_f32_e32 v11, v11, v11
	v_mul_f32_e32 v18, v0, v0
	v_mul_f32_e32 v19, v1, v1
	v_mul_f32_e32 v20, v2, v2
	v_mul_f32_e32 v21, v3, v3
	v_cvt_pk_bf16_f32 v0, v12, v13
	v_cvt_pk_bf16_f32 v1, v14, v15
	v_cvt_pk_bf16_f32 v2, v8, v9
	v_cvt_pk_bf16_f32 v3, v10, v11
	s_mov_b64 s[4:5], -1
	v_mul_f32_e32 v4, v4, v4
	v_mul_f32_e32 v5, v5, v5
	v_mul_f32_e32 v6, v6, v6
	v_mul_f32_e32 v7, v7, v7
	global_store_dwordx4 v[16:17], v[0:3], off
	s_nop 1
	v_cvt_pk_bf16_f32 v0, v4, v5
	v_cvt_pk_bf16_f32 v1, v6, v7
	v_cvt_pk_bf16_f32 v2, v18, v19
	v_cvt_pk_bf16_f32 v3, v20, v21
	global_store_dwordx4 v[16:17], v[0:3], off offset:256
	s_cbranch_vccnz .LBB0_720
	s_andn2_b64 vcc, exec, s[10:11]
	s_cbranch_vccnz .LBB0_719
	s_barrier
	s_branch .LBB0_719

; __device__ __forceinline__ u32x4 pack8(const f32x4 a, const f32x4 b) { u32x4 w; w.x = cvt_pk_bf16(a[0], a[1]); w.y = cvt_pk_bf16(a[2], a[3]); w.z = cvt_pk_bf16(b[0], b[1]); w.w = cvt_pk_bf16(b[2], b[3]); return w; }
;     __device__ __forceinline__ void operator()(const f32x4 (&acc)[2][2][4][2], const Unit& u, int wr, int wc, int fr, int fq) const {
;     ...
;         for (int ai = 0; ai < 2; ++ai)
; #pragma unroll
;             for (int m = 0; m < 4; ++m) {
;                 const int row = u.pm * BM + ai * HALF + wr * 64 + m * 16 + fr;
;                 const float rstd = rsqrtf(ssq[row] * (1.0f / 2048.0f) + EPS);
; #pragma unroll
;                 for (int bj = 0; bj < 2; ++bj) {
;                     const int col = u.pn * BM + bj * HALF + wc * 32 + 8 * fq;
;                     f32x4 v0 = acc[ai][bj][m][0] * rstd, v1 = acc[ai][bj][m][1] * rstd;
; #pragma unroll
;                     for (int k = 0; k < 4; ++k) { const float a = fmaxf(v0[k], 0.f), b = fmaxf(v1[k], 0.f); v0[k] = a * a; v1[k] = b * b; }
;                     *(u32x4*)(HID + (size_t)row * 8192 + col) = pack8(v0, v1);
.LBB0_924:
	s_lshl_b32 s19, s26, 8
	v_mov_b32_e32 v144, v148
	v_mov_b32_e32 v155, v149
	s_add_i32 s19, s19, s40
	s_nop 0
	v_add_u32_e32 v146, s19, v144
	v_ashrrev_i32_e32 v147, 31, v146
	v_lshl_add_u64 v[144:145], v[146:147], 2, s[94:95]
	v_lshlrev_b32_e32 v248, 2, v146
	global_load_dword v240, v248, s[94:95]
	global_load_dword v241, v248, s[94:95] offset:64
	global_load_dword v242, v248, s[94:95] offset:128
	global_load_dword v243, v248, s[94:95] offset:192
	global_load_dword v244, v248, s[94:95] offset:512
	global_load_dword v245, v248, s[94:95] offset:576
	global_load_dword v246, v248, s[94:95] offset:640
	global_load_dword v247, v248, s[94:95] offset:704
	s_lshl_b32 s19, s48, 8
	s_or_b32 s19, s19, s41
	v_lshlrev_b64 v[158:159], 14, v[146:147]
	v_lshl_add_u32 v144, v155, 3, s19
	v_ashrrev_i32_e32 v145, 31, v144
	v_add_u32_e32 v156, 16, v146
	v_lshlrev_b64 v[144:145], 1, v[144:145]
	v_lshl_add_u64 v[158:159], s[12:13], 0, v[158:159]
	v_ashrrev_i32_e32 v157, 31, v156
	v_lshl_add_u64 v[158:159], v[158:159], 0, v[144:145]
	s_waitcnt vmcnt(0)
	v_fmamk_f32 v147, v240, 0x3a000000, v154
	v_mul_f32_e32 v155, 0x4b800000, v147
	v_cmp_gt_f32_e32 vcc, s47, v147
	v_lshl_add_u64 v[160:161], v[156:157], 2, s[94:95]
	s_nop 0
	v_cndmask_b32_e32 v147, v147, v155, vcc
	v_rsq_f32_e32 v147, v147
	s_nop 0
	v_mul_f32_e32 v155, 0x45800000, v147
	v_cndmask_b32_e32 v162, v147, v155, vcc
	v_pk_mul_f32 v[126:127], v[126:127], v[162:163] op_sel_hi:[1,0]
	v_pk_mul_f32 v[124:125], v[124:125], v[162:163] op_sel_hi:[1,0]
	v_pk_mul_f32 v[122:123], v[122:123], v[162:163] op_sel_hi:[1,0]
	v_pk_mul_f32 v[120:121], v[120:121], v[162:163] op_sel_hi:[1,0]
	v_pk_mul_f32 v[114:115], v[114:115], v[162:163] op_sel_hi:[1,0]
	v_pk_mul_f32 v[112:113], v[112:113], v[162:163] op_sel_hi:[1,0]
	v_pk_mul_f32 v[118:119], v[118:119], v[162:163] op_sel_hi:[1,0]
	v_pk_mul_f32 v[116:117], v[116:117], v[162:163] op_sel_hi:[1,0]
	v_max_f32_e32 v124, 0, v124
	v_max_f32_e32 v120, 0, v120
	v_max_f32_e32 v125, 0, v125
	v_max_f32_e32 v121, 0, v121
	v_max_f32_e32 v126, 0, v126
	v_max_f32_e32 v122, 0, v122
	v_max_f32_e32 v127, 0, v127
	v_max_f32_e32 v123, 0, v123
	v_max_f32_e32 v112, 0, v112
	v_max_f32_e32 v113, 0, v113
	v_max_f32_e32 v114, 0, v114
	v_max_f32_e32 v115, 0, v115
	v_max_f32_e32 v116, 0, v116
	v_max_f32_e32 v117, 0, v117
	v_max_f32_e32 v118, 0, v118
	v_max_f32_e32 v119, 0, v119
	v_mul_f32_e32 v124, v124, v124
	v_mul_f32_e32 v120, v120, v120
	v_mul_f32_e32 v125, v125, v125
	v_mul_f32_e32 v121, v121, v121
	v_mul_f32_e32 v126, v126, v126
	v_mul_f32_e32 v122, v122, v122
	v_mul_f32_e32 v127, v127, v127
	v_mul_f32_e32 v123, v123, v123
	v_mul_f32_e32 v147, v112, v112
	v_mul_f32_e32 v155, v113, v113
	v_mul_f32_e32 v162, v114, v114
	v_mul_f32_e32 v163, v115, v115
	v_cvt_pk_bf16_f32 v112, v124, v125
	v_cvt_pk_bf16_f32 v113, v126, v127
	v_cvt_pk_bf16_f32 v114, v120, v121
	v_cvt_pk_bf16_f32 v115, v122, v123
	v_mul_f32_e32 v116, v116, v116
	v_mul_f32_e32 v117, v117, v117
	v_mul_f32_e32 v118, v118, v118
	v_mul_f32_e32 v119, v119, v119
	global_store_dwordx4 v[158:159], v[112:115], off
	s_nop 1
	v_cvt_pk_bf16_f32 v112, v116, v117
	v_cvt_pk_bf16_f32 v113, v118, v119
	v_cvt_pk_bf16_f32 v114, v147, v155
	v_cvt_pk_bf16_f32 v115, v162, v163
	global_store_dwordx4 v[158:159], v[112:115], off offset:256
	s_waitcnt vmcnt(0)
	v_fmamk_f32 v116, v241, 0x3a000000, v154
	v_mul_f32_e32 v117, 0x4b800000, v116
	v_cmp_gt_f32_e32 vcc, s47, v116
	v_lshlrev_b64 v[114:115], 14, v[156:157]
	v_add_u32_e32 v112, 32, v146
	v_cndmask_b32_e32 v116, v116, v117, vcc
	v_rsq_f32_e32 v118, v116
	v_lshl_add_u64 v[114:115], s[12:13], 0, v[114:115]
	v_ashrrev_i32_e32 v113, 31, v112
	v_lshl_add_u64 v[114:115], v[114:115], 0, v[144:145]
	v_mul_f32_e32 v119, 0x45800000, v118
	v_cndmask_b32_e32 v118, v118, v119, vcc
	v_pk_mul_f32 v[110:111], v[110:111], v[118:119] op_sel_hi:[1,0]
	v_pk_mul_f32 v[108:109], v[108:109], v[118:119] op_sel_hi:[1,0]
	v_pk_mul_f32 v[106:107], v[106:107], v[118:119] op_sel_hi:[1,0]
	v_pk_mul_f32 v[104:105], v[104:105], v[118:119] op_sel_hi:[1,0]
	v_pk_mul_f32 v[98:99], v[98:99], v[118:119] op_sel_hi:[1,0]
	v_pk_mul_f32 v[96:97], v[96:97], v[118:119] op_sel_hi:[1,0]
	v_pk_mul_f32 v[102:103], v[102:103], v[118:119] op_sel_hi:[1,0]
	v_pk_mul_f32 v[100:101], v[100:101], v[118:119] op_sel_hi:[1,0]
	v_max_f32_e32 v108, 0, v108
	v_max_f32_e32 v104, 0, v104
	v_max_f32_e32 v109, 0, v109
	v_max_f32_e32 v105, 0, v105
	v_max_f32_e32 v110, 0, v110
	v_max_f32_e32 v106, 0, v106
	v_max_f32_e32 v111, 0, v111
	v_max_f32_e32 v107, 0, v107
	v_max_f32_e32 v96, 0, v96
	v_max_f32_e32 v97, 0, v97
	v_max_f32_e32 v98, 0, v98
	v_max_f32_e32 v99, 0, v99
	v_max_f32_e32 v100, 0, v100
	v_max_f32_e32 v101, 0, v101
	v_max_f32_e32 v102, 0, v102
	v_max_f32_e32 v103, 0, v103
	v_mul_f32_e32 v108, v108, v108
	v_mul_f32_e32 v104, v104, v104
	v_mul_f32_e32 v109, v109, v109
	v_mul_f32_e32 v105, v105, v105
	v_mul_f32_e32 v110, v110, v110
	v_mul_f32_e32 v106, v106, v106
	v_mul_f32_e32 v111, v111, v111
	v_mul_f32_e32 v107, v107, v107
	v_mul_f32_e32 v118, v96, v96
	v_mul_f32_e32 v119, v97, v97
	v_mul_f32_e32 v120, v98, v98
	v_mul_f32_e32 v121, v99, v99
	v_cvt_pk_bf16_f32 v96, v108, v109
	v_cvt_pk_bf16_f32 v97, v110, v111
	v_cvt_pk_bf16_f32 v98, v104, v105
	v_cvt_pk_bf16_f32 v99, v106, v107
	v_lshl_add_u64 v[116:117], v[112:113], 2, s[94:95]
	v_mul_f32_e32 v100, v100, v100
	v_mul_f32_e32 v101, v101, v101
	v_mul_f32_e32 v102, v102, v102
	v_mul_f32_e32 v103, v103, v103
	global_store_dwordx4 v[114:115], v[96:99], off
	s_nop 1
	v_cvt_pk_bf16_f32 v96, v100, v101
	v_cvt_pk_bf16_f32 v97, v102, v103
	v_cvt_pk_bf16_f32 v98, v118, v119
	v_cvt_pk_bf16_f32 v99, v120, v121
	global_store_dwordx4 v[114:115], v[96:99], off offset:256
	s_waitcnt vmcnt(0)
; __device__ __forceinline__ u32x4 pack8(const f32x4 a, const f32x4 b) { u32x4 w; w.x = cvt_pk_bf16(a[0], a[1]); w.y = cvt_pk_bf16(a[2], a[3]); w.z = cvt_pk_bf16(b[0], b[1]); w.w = cvt_pk_bf16(b[2], b[3]); return w; }
;     __device__ __forceinline__ void operator()(const f32x4 (&acc)[2][2][4][2], const Unit& u, int wr, int wc, int fr, int fq) const {
;     ...
;         for (int ai = 0; ai < 2; ++ai)
; #pragma unroll
;             for (int m = 0; m < 4; ++m) {
;                 const int row = u.pm * BM + ai * HALF + wr * 64 + m * 16 + fr;
;                 const float rstd = rsqrtf(ssq[row] * (1.0f / 2048.0f) + EPS);
; #pragma unroll
;                 for (int bj = 0; bj < 2; ++bj) {
;                     const int col = u.pn * BM + bj * HALF + wc * 32 + 8 * fq;
;                     f32x4 v0 = acc[ai][bj][m][0] * rstd, v1 = acc[ai][bj][m][1] * rstd;
; #pragma unroll
;                     for (int k = 0; k < 4; ++k) { const float a = fmaxf(v0[k], 0.f), b = fmaxf(v1[k], 0.f); v0[k] = a * a; v1[k] = b * b; }
;                     *(u32x4*)(HID + (size_t)row * 8192 + col) = pack8(v0, v1);
	v_fmamk_f32 v100, v242, 0x3a000000, v154
	v_mul_f32_e32 v101, 0x4b800000, v100
	v_cmp_gt_f32_e32 vcc, s47, v100
	v_lshlrev_b64 v[98:99], 14, v[112:113]
	v_add_u32_e32 v96, 48, v146
	v_cndmask_b32_e32 v100, v100, v101, vcc
	v_rsq_f32_e32 v102, v100
	v_lshl_add_u64 v[98:99], s[12:13], 0, v[98:99]
	v_ashrrev_i32_e32 v97, 31, v96
	v_lshl_add_u64 v[98:99], v[98:99], 0, v[144:145]
	v_mul_f32_e32 v103, 0x45800000, v102
	v_cndmask_b32_e32 v102, v102, v103, vcc
	v_pk_mul_f32 v[94:95], v[94:95], v[102:103] op_sel_hi:[1,0]
	v_pk_mul_f32 v[92:93], v[92:93], v[102:103] op_sel_hi:[1,0]
	v_pk_mul_f32 v[90:91], v[90:91], v[102:103] op_sel_hi:[1,0]
	v_pk_mul_f32 v[88:89], v[88:89], v[102:103] op_sel_hi:[1,0]
	v_pk_mul_f32 v[82:83], v[82:83], v[102:103] op_sel_hi:[1,0]
	v_pk_mul_f32 v[80:81], v[80:81], v[102:103] op_sel_hi:[1,0]
	v_pk_mul_f32 v[86:87], v[86:87], v[102:103] op_sel_hi:[1,0]
	v_pk_mul_f32 v[84:85], v[84:85], v[102:103] op_sel_hi:[1,0]
	v_max_f32_e32 v92, 0, v92
	v_max_f32_e32 v88, 0, v88
	v_max_f32_e32 v93, 0, v93
	v_max_f32_e32 v89, 0, v89
	v_max_f32_e32 v94, 0, v94
	v_max_f32_e32 v90, 0, v90
	v_max_f32_e32 v95, 0, v95
	v_max_f32_e32 v91, 0, v91
	v_max_f32_e32 v80, 0, v80
	v_max_f32_e32 v81, 0, v81
	v_max_f32_e32 v82, 0, v82
	v_max_f32_e32 v83, 0, v83
	v_max_f32_e32 v84, 0, v84
	v_max_f32_e32 v85, 0, v85
	v_max_f32_e32 v86, 0, v86
	v_max_f32_e32 v87, 0, v87
	v_mul_f32_e32 v92, v92, v92
	v_mul_f32_e32 v88, v88, v88
	v_mul_f32_e32 v93, v93, v93
	v_mul_f32_e32 v89, v89, v89
	v_mul_f32_e32 v94, v94, v94
	v_mul_f32_e32 v90, v90, v90
	v_mul_f32_e32 v95, v95, v95
	v_mul_f32_e32 v91, v91, v91
	v_mul_f32_e32 v102, v80, v80
	v_mul_f32_e32 v103, v81, v81
	v_mul_f32_e32 v104, v82, v82
	v_mul_f32_e32 v105, v83, v83
	v_cvt_pk_bf16_f32 v80, v92, v93
	v_cvt_pk_bf16_f32 v81, v94, v95
	v_cvt_pk_bf16_f32 v82, v88, v89
	v_cvt_pk_bf16_f32 v83, v90, v91
	v_lshl_add_u64 v[100:101], v[96:97], 2, s[94:95]
	v_mul_f32_e32 v84, v84, v84
	v_mul_f32_e32 v85, v85, v85
	v_mul_f32_e32 v86, v86, v86
	v_mul_f32_e32 v87, v87, v87
	global_store_dwordx4 v[98:99], v[80:83], off
	s_nop 1
	v_cvt_pk_bf16_f32 v80, v84, v85
	v_cvt_pk_bf16_f32 v81, v86, v87
	v_cvt_pk_bf16_f32 v82, v102, v103
	v_cvt_pk_bf16_f32 v83, v104, v105
	global_store_dwordx4 v[98:99], v[80:83], off offset:256
	s_waitcnt vmcnt(0)
	v_fmamk_f32 v84, v243, 0x3a000000, v154
	v_mul_f32_e32 v85, 0x4b800000, v84
	v_cmp_gt_f32_e32 vcc, s47, v84
	v_lshlrev_b64 v[82:83], 14, v[96:97]
	v_add_u32_e32 v80, 0x80, v146
	v_cndmask_b32_e32 v84, v84, v85, vcc
	v_rsq_f32_e32 v86, v84
	v_lshl_add_u64 v[82:83], s[12:13], 0, v[82:83]
	v_ashrrev_i32_e32 v81, 31, v80
	v_lshl_add_u64 v[82:83], v[82:83], 0, v[144:145]
	v_mul_f32_e32 v87, 0x45800000, v86
	v_cndmask_b32_e32 v86, v86, v87, vcc
	v_pk_mul_f32 v[78:79], v[78:79], v[86:87] op_sel_hi:[1,0]
	v_pk_mul_f32 v[76:77], v[76:77], v[86:87] op_sel_hi:[1,0]
	v_pk_mul_f32 v[74:75], v[74:75], v[86:87] op_sel_hi:[1,0]
	v_pk_mul_f32 v[72:73], v[72:73], v[86:87] op_sel_hi:[1,0]
	v_pk_mul_f32 v[66:67], v[66:67], v[86:87] op_sel_hi:[1,0]
	v_pk_mul_f32 v[64:65], v[64:65], v[86:87] op_sel_hi:[1,0]
	v_pk_mul_f32 v[70:71], v[70:71], v[86:87] op_sel_hi:[1,0]
	v_pk_mul_f32 v[68:69], v[68:69], v[86:87] op_sel_hi:[1,0]
	v_max_f32_e32 v76, 0, v76
	v_max_f32_e32 v72, 0, v72
	v_max_f32_e32 v77, 0, v77
	v_max_f32_e32 v73, 0, v73
	v_max_f32_e32 v78, 0, v78
	v_max_f32_e32 v74, 0, v74
	v_max_f32_e32 v79, 0, v79
	v_max_f32_e32 v75, 0, v75
	v_max_f32_e32 v64, 0, v64
	v_max_f32_e32 v65, 0, v65
	v_max_f32_e32 v66, 0, v66
	v_max_f32_e32 v67, 0, v67
	v_max_f32_e32 v68, 0, v68
	v_max_f32_e32 v69, 0, v69
	v_max_f32_e32 v70, 0, v70
	v_max_f32_e32 v71, 0, v71
	v_mul_f32_e32 v76, v76, v76
	v_mul_f32_e32 v72, v72, v72
	v_mul_f32_e32 v77, v77, v77
	v_mul_f32_e32 v73, v73, v73
	v_mul_f32_e32 v78, v78, v78
	v_mul_f32_e32 v74, v74, v74
	v_mul_f32_e32 v79, v79, v79
	v_mul_f32_e32 v75, v75, v75
	v_mul_f32_e32 v86, v64, v64
	v_mul_f32_e32 v87, v65, v65
	v_mul_f32_e32 v88, v66, v66
	v_mul_f32_e32 v89, v67, v67
	v_cvt_pk_bf16_f32 v64, v76, v77
	v_cvt_pk_bf16_f32 v65, v78, v79
	v_cvt_pk_bf16_f32 v66, v72, v73
	v_cvt_pk_bf16_f32 v67, v74, v75
	v_lshl_add_u64 v[84:85], v[80:81], 2, s[94:95]
	v_mul_f32_e32 v68, v68, v68
	v_mul_f32_e32 v69, v69, v69
	v_mul_f32_e32 v70, v70, v70
	v_mul_f32_e32 v71, v71, v71
	global_store_dwordx4 v[82:83], v[64:67], off
	s_nop 1
	v_cvt_pk_bf16_f32 v64, v68, v69
	v_cvt_pk_bf16_f32 v65, v70, v71
	v_cvt_pk_bf16_f32 v66, v86, v87
	v_cvt_pk_bf16_f32 v67, v88, v89
	global_store_dwordx4 v[82:83], v[64:67], off offset:256
	s_waitcnt vmcnt(0)
; __device__ __forceinline__ u32x4 pack8(const f32x4 a, const f32x4 b) { u32x4 w; w.x = cvt_pk_bf16(a[0], a[1]); w.y = cvt_pk_bf16(a[2], a[3]); w.z = cvt_pk_bf16(b[0], b[1]); w.w = cvt_pk_bf16(b[2], b[3]); return w; }
;     __device__ __forceinline__ void operator()(const f32x4 (&acc)[2][2][4][2], const Unit& u, int wr, int wc, int fr, int fq) const {
;     ...
;         for (int ai = 0; ai < 2; ++ai)
; #pragma unroll
;             for (int m = 0; m < 4; ++m) {
;                 const int row = u.pm * BM + ai * HALF + wr * 64 + m * 16 + fr;
;                 const float rstd = rsqrtf(ssq[row] * (1.0f / 2048.0f) + EPS);
; #pragma unroll
;                 for (int bj = 0; bj < 2; ++bj) {
;                     const int col = u.pn * BM + bj * HALF + wc * 32 + 8 * fq;
;                     f32x4 v0 = acc[ai][bj][m][0] * rstd, v1 = acc[ai][bj][m][1] * rstd;
; #pragma unroll
;                     for (int k = 0; k < 4; ++k) { const float a = fmaxf(v0[k], 0.f), b = fmaxf(v1[k], 0.f); v0[k] = a * a; v1[k] = b * b; }
;                     *(u32x4*)(HID + (size_t)row * 8192 + col) = pack8(v0, v1);
	v_fmamk_f32 v68, v244, 0x3a000000, v154
	v_mul_f32_e32 v69, 0x4b800000, v68
	v_cmp_gt_f32_e32 vcc, s47, v68
	v_lshlrev_b64 v[66:67], 14, v[80:81]
	v_add_u32_e32 v64, 0x90, v146
	v_cndmask_b32_e32 v68, v68, v69, vcc
	v_rsq_f32_e32 v70, v68
	v_lshl_add_u64 v[66:67], s[12:13], 0, v[66:67]
	v_ashrrev_i32_e32 v65, 31, v64
	v_lshl_add_u64 v[66:67], v[66:67], 0, v[144:145]
	v_mul_f32_e32 v71, 0x45800000, v70
	v_cndmask_b32_e32 v70, v70, v71, vcc
	v_pk_mul_f32 v[62:63], v[62:63], v[70:71] op_sel_hi:[1,0]
	v_pk_mul_f32 v[60:61], v[60:61], v[70:71] op_sel_hi:[1,0]
	v_pk_mul_f32 v[58:59], v[58:59], v[70:71] op_sel_hi:[1,0]
	v_pk_mul_f32 v[56:57], v[56:57], v[70:71] op_sel_hi:[1,0]
	v_pk_mul_f32 v[50:51], v[50:51], v[70:71] op_sel_hi:[1,0]
	v_pk_mul_f32 v[48:49], v[48:49], v[70:71] op_sel_hi:[1,0]
	v_pk_mul_f32 v[54:55], v[54:55], v[70:71] op_sel_hi:[1,0]
	v_pk_mul_f32 v[52:53], v[52:53], v[70:71] op_sel_hi:[1,0]
	v_max_f32_e32 v60, 0, v60
	v_max_f32_e32 v56, 0, v56
	v_max_f32_e32 v61, 0, v61
	v_max_f32_e32 v57, 0, v57
	v_max_f32_e32 v62, 0, v62
	v_max_f32_e32 v58, 0, v58
	v_max_f32_e32 v63, 0, v63
	v_max_f32_e32 v59, 0, v59
	v_max_f32_e32 v48, 0, v48
	v_max_f32_e32 v49, 0, v49
	v_max_f32_e32 v50, 0, v50
	v_max_f32_e32 v51, 0, v51
	v_max_f32_e32 v52, 0, v52
	v_max_f32_e32 v53, 0, v53
	v_max_f32_e32 v54, 0, v54
	v_max_f32_e32 v55, 0, v55
	v_mul_f32_e32 v60, v60, v60
	v_mul_f32_e32 v56, v56, v56
	v_mul_f32_e32 v61, v61, v61
	v_mul_f32_e32 v57, v57, v57
	v_mul_f32_e32 v62, v62, v62
	v_mul_f32_e32 v58, v58, v58
	v_mul_f32_e32 v63, v63, v63
	v_mul_f32_e32 v59, v59, v59
	v_mul_f32_e32 v70, v48, v48
	v_mul_f32_e32 v71, v49, v49
	v_mul_f32_e32 v72, v50, v50
	v_mul_f32_e32 v73, v51, v51
	v_cvt_pk_bf16_f32 v48, v60, v61
	v_cvt_pk_bf16_f32 v49, v62, v63
	v_cvt_pk_bf16_f32 v50, v56, v57
	v_cvt_pk_bf16_f32 v51, v58, v59
	v_lshl_add_u64 v[68:69], v[64:65], 2, s[94:95]
	v_mul_f32_e32 v52, v52, v52
	v_mul_f32_e32 v53, v53, v53
	v_mul_f32_e32 v54, v54, v54
	v_mul_f32_e32 v55, v55, v55
	global_store_dwordx4 v[66:67], v[48:51], off
	s_nop 1
	v_cvt_pk_bf16_f32 v48, v52, v53
	v_cvt_pk_bf16_f32 v49, v54, v55
	v_cvt_pk_bf16_f32 v50, v70, v71
	v_cvt_pk_bf16_f32 v51, v72, v73
	global_store_dwordx4 v[66:67], v[48:51], off offset:256
	s_waitcnt vmcnt(0)
	v_fmamk_f32 v52, v245, 0x3a000000, v154
	v_mul_f32_e32 v53, 0x4b800000, v52
	v_cmp_gt_f32_e32 vcc, s47, v52
	v_lshlrev_b64 v[50:51], 14, v[64:65]
	v_add_u32_e32 v48, 0xa0, v146
	v_cndmask_b32_e32 v52, v52, v53, vcc
	v_rsq_f32_e32 v54, v52
	v_lshl_add_u64 v[50:51], s[12:13], 0, v[50:51]
	v_ashrrev_i32_e32 v49, 31, v48
	v_lshl_add_u64 v[50:51], v[50:51], 0, v[144:145]
	v_mul_f32_e32 v55, 0x45800000, v54
	v_cndmask_b32_e32 v54, v54, v55, vcc
	v_pk_mul_f32 v[46:47], v[46:47], v[54:55] op_sel_hi:[1,0]
	v_pk_mul_f32 v[44:45], v[44:45], v[54:55] op_sel_hi:[1,0]
	v_pk_mul_f32 v[42:43], v[42:43], v[54:55] op_sel_hi:[1,0]
	v_pk_mul_f32 v[40:41], v[40:41], v[54:55] op_sel_hi:[1,0]
	v_pk_mul_f32 v[34:35], v[34:35], v[54:55] op_sel_hi:[1,0]
	v_pk_mul_f32 v[32:33], v[32:33], v[54:55] op_sel_hi:[1,0]
	v_pk_mul_f32 v[38:39], v[38:39], v[54:55] op_sel_hi:[1,0]
	v_pk_mul_f32 v[36:37], v[36:37], v[54:55] op_sel_hi:[1,0]
	v_max_f32_e32 v44, 0, v44
	v_max_f32_e32 v40, 0, v40
	v_max_f32_e32 v45, 0, v45
	v_max_f32_e32 v41, 0, v41
	v_max_f32_e32 v46, 0, v46
	v_max_f32_e32 v42, 0, v42
	v_max_f32_e32 v47, 0, v47
	v_max_f32_e32 v43, 0, v43
	v_max_f32_e32 v32, 0, v32
	v_max_f32_e32 v33, 0, v33
	v_max_f32_e32 v34, 0, v34
	v_max_f32_e32 v35, 0, v35
	v_max_f32_e32 v36, 0, v36
	v_max_f32_e32 v37, 0, v37
	v_max_f32_e32 v38, 0, v38
	v_max_f32_e32 v39, 0, v39
	v_mul_f32_e32 v44, v44, v44
	v_mul_f32_e32 v40, v40, v40
	v_mul_f32_e32 v45, v45, v45
	v_mul_f32_e32 v41, v41, v41
	v_mul_f32_e32 v46, v46, v46
	v_mul_f32_e32 v42, v42, v42
	v_mul_f32_e32 v47, v47, v47
	v_mul_f32_e32 v43, v43, v43
	v_mul_f32_e32 v54, v32, v32
	v_mul_f32_e32 v55, v33, v33
	v_mul_f32_e32 v56, v34, v34
	v_mul_f32_e32 v57, v35, v35
	v_cvt_pk_bf16_f32 v32, v44, v45
	v_cvt_pk_bf16_f32 v33, v46, v47
	v_cvt_pk_bf16_f32 v34, v40, v41
	v_cvt_pk_bf16_f32 v35, v42, v43
	v_lshl_add_u64 v[52:53], v[48:49], 2, s[94:95]
	v_mul_f32_e32 v36, v36, v36
	v_mul_f32_e32 v37, v37, v37
	v_mul_f32_e32 v38, v38, v38
	v_mul_f32_e32 v39, v39, v39
	global_store_dwordx4 v[50:51], v[32:35], off
	s_nop 1
	v_cvt_pk_bf16_f32 v32, v36, v37
	v_cvt_pk_bf16_f32 v33, v38, v39
	v_cvt_pk_bf16_f32 v34, v54, v55
	v_cvt_pk_bf16_f32 v35, v56, v57
	global_store_dwordx4 v[50:51], v[32:35], off offset:256
	s_waitcnt vmcnt(0)
; __device__ __forceinline__ u32x4 pack8(const f32x4 a, const f32x4 b) { u32x4 w; w.x = cvt_pk_bf16(a[0], a[1]); w.y = cvt_pk_bf16(a[2], a[3]); w.z = cvt_pk_bf16(b[0], b[1]); w.w = cvt_pk_bf16(b[2], b[3]); return w; }
; #define PG8_BAR __builtin_amdgcn_s_barrier()
; template <class Epi, class Sched, bool ALIGN_EPI = false, bool SP2 = false>
; __device__ __forceinline__ void gemm_phase(PG8_LAS unsigned char* lds, const Gemm g, const Sched& S, const Epi& E) {
;     ...
;         if (!has_next) break;
; #pragma unroll
;         for (int a = 0; a < 2; ++a)
; #pragma unroll
;             for (int b = 0; b < 2; ++b)
; #pragma unroll
;                 for (int m = 0; m < 4; ++m)
; #pragma unroll
;                     for (int n = 0; n < 2; ++n) acc[a][b][m][n] = (f32x4){0.f, 0.f, 0.f, 0.f};
;         cur = nxt; cA = nA; cB = nB; ++ui;
;         if constexpr (ALIGN_EPI) { if (wr == 1) PG8_BAR; }
;     __device__ __forceinline__ void operator()(const f32x4 (&acc)[2][2][4][2], const Unit& u, int wr, int wc, int fr, int fq) const {
;     ...
;         for (int ai = 0; ai < 2; ++ai)
; #pragma unroll
;             for (int m = 0; m < 4; ++m) {
;                 const int row = u.pm * BM + ai * HALF + wr * 64 + m * 16 + fr;
;                 const float rstd = rsqrtf(ssq[row] * (1.0f / 2048.0f) + EPS);
; #pragma unroll
;                 for (int bj = 0; bj < 2; ++bj) {
;                     const int col = u.pn * BM + bj * HALF + wc * 32 + 8 * fq;
;                     f32x4 v0 = acc[ai][bj][m][0] * rstd, v1 = acc[ai][bj][m][1] * rstd;
; #pragma unroll
;                     for (int k = 0; k < 4; ++k) { const float a = fmaxf(v0[k], 0.f), b = fmaxf(v1[k], 0.f); v0[k] = a * a; v1[k] = b * b; }
;                     *(u32x4*)(HID + (size_t)row * 8192 + col) = pack8(v0, v1);
	v_fmamk_f32 v36, v246, 0x3a000000, v154
	v_mul_f32_e32 v37, 0x4b800000, v36
	v_cmp_gt_f32_e32 vcc, s47, v36
	v_lshlrev_b64 v[34:35], 14, v[48:49]
	v_add_u32_e32 v32, 0xb0, v146
	v_cndmask_b32_e32 v36, v36, v37, vcc
	v_rsq_f32_e32 v38, v36
	v_lshl_add_u64 v[34:35], s[12:13], 0, v[34:35]
	v_ashrrev_i32_e32 v33, 31, v32
	v_lshl_add_u64 v[34:35], v[34:35], 0, v[144:145]
	v_mul_f32_e32 v39, 0x45800000, v38
	v_cndmask_b32_e32 v38, v38, v39, vcc
	v_pk_mul_f32 v[30:31], v[30:31], v[38:39] op_sel_hi:[1,0]
	v_pk_mul_f32 v[28:29], v[28:29], v[38:39] op_sel_hi:[1,0]
	v_pk_mul_f32 v[26:27], v[26:27], v[38:39] op_sel_hi:[1,0]
	v_pk_mul_f32 v[24:25], v[24:25], v[38:39] op_sel_hi:[1,0]
	v_pk_mul_f32 v[18:19], v[18:19], v[38:39] op_sel_hi:[1,0]
	v_pk_mul_f32 v[16:17], v[16:17], v[38:39] op_sel_hi:[1,0]
	v_pk_mul_f32 v[22:23], v[22:23], v[38:39] op_sel_hi:[1,0]
	v_pk_mul_f32 v[20:21], v[20:21], v[38:39] op_sel_hi:[1,0]
	v_max_f32_e32 v28, 0, v28
	v_max_f32_e32 v24, 0, v24
	v_max_f32_e32 v29, 0, v29
	v_max_f32_e32 v25, 0, v25
	v_max_f32_e32 v30, 0, v30
	v_max_f32_e32 v26, 0, v26
	v_max_f32_e32 v31, 0, v31
	v_max_f32_e32 v27, 0, v27
	v_max_f32_e32 v16, 0, v16
	v_max_f32_e32 v17, 0, v17
	v_max_f32_e32 v18, 0, v18
	v_max_f32_e32 v19, 0, v19
	v_max_f32_e32 v20, 0, v20
	v_max_f32_e32 v21, 0, v21
	v_max_f32_e32 v22, 0, v22
	v_max_f32_e32 v23, 0, v23
	v_mul_f32_e32 v28, v28, v28
	v_mul_f32_e32 v24, v24, v24
	v_mul_f32_e32 v29, v29, v29
	v_mul_f32_e32 v25, v25, v25
	v_mul_f32_e32 v30, v30, v30
	v_mul_f32_e32 v26, v26, v26
	v_mul_f32_e32 v31, v31, v31
	v_mul_f32_e32 v27, v27, v27
	v_mul_f32_e32 v38, v16, v16
	v_mul_f32_e32 v39, v17, v17
	v_mul_f32_e32 v40, v18, v18
	v_mul_f32_e32 v41, v19, v19
	v_cvt_pk_bf16_f32 v16, v28, v29
	v_cvt_pk_bf16_f32 v17, v30, v31
	v_cvt_pk_bf16_f32 v18, v24, v25
	v_cvt_pk_bf16_f32 v19, v26, v27
	v_lshl_add_u64 v[36:37], v[32:33], 2, s[94:95]
	v_mul_f32_e32 v20, v20, v20
	v_mul_f32_e32 v21, v21, v21
	v_mul_f32_e32 v22, v22, v22
	v_mul_f32_e32 v23, v23, v23
	global_store_dwordx4 v[34:35], v[16:19], off
	s_andn2_b64 vcc, exec, s[4:5]
	s_nop 0
	v_cvt_pk_bf16_f32 v16, v20, v21
	v_cvt_pk_bf16_f32 v17, v22, v23
	v_cvt_pk_bf16_f32 v18, v38, v39
	v_cvt_pk_bf16_f32 v19, v40, v41
	global_store_dwordx4 v[34:35], v[16:19], off offset:256
	s_waitcnt vmcnt(0)
	v_fmamk_f32 v16, v247, 0x3a000000, v154
	v_mul_f32_e32 v17, 0x4b800000, v16
	v_cmp_gt_f32_e64 s[4:5], s47, v16
	s_nop 1
	v_cndmask_b32_e64 v16, v16, v17, s[4:5]
	v_rsq_f32_e32 v18, v16
	v_lshlrev_b64 v[16:17], 14, v[32:33]
	v_lshl_add_u64 v[16:17], s[12:13], 0, v[16:17]
	v_lshl_add_u64 v[16:17], v[16:17], 0, v[144:145]
	v_mul_f32_e32 v19, 0x45800000, v18
	v_cndmask_b32_e64 v18, v18, v19, s[4:5]
	v_pk_mul_f32 v[14:15], v[14:15], v[18:19] op_sel_hi:[1,0]
	v_pk_mul_f32 v[12:13], v[12:13], v[18:19] op_sel_hi:[1,0]
	v_pk_mul_f32 v[10:11], v[10:11], v[18:19] op_sel_hi:[1,0]
	v_pk_mul_f32 v[8:9], v[8:9], v[18:19] op_sel_hi:[1,0]
	v_pk_mul_f32 v[2:3], v[2:3], v[18:19] op_sel_hi:[1,0]
	v_pk_mul_f32 v[0:1], v[0:1], v[18:19] op_sel_hi:[1,0]
	v_pk_mul_f32 v[6:7], v[6:7], v[18:19] op_sel_hi:[1,0]
	v_pk_mul_f32 v[4:5], v[4:5], v[18:19] op_sel_hi:[1,0]
	v_max_f32_e32 v12, 0, v12
	v_max_f32_e32 v8, 0, v8
	v_max_f32_e32 v13, 0, v13
	v_max_f32_e32 v9, 0, v9
	v_max_f32_e32 v14, 0, v14
	v_max_f32_e32 v10, 0, v10
	v_max_f32_e32 v15, 0, v15
	v_max_f32_e32 v11, 0, v11
	v_max_f32_e32 v0, 0, v0
	v_max_f32_e32 v1, 0, v1
	v_max_f32_e32 v2, 0, v2
	v_max_f32_e32 v3, 0, v3
	v_max_f32_e32 v4, 0, v4
	v_max_f32_e32 v5, 0, v5
	v_max_f32_e32 v6, 0, v6
	v_max_f32_e32 v7, 0, v7
	v_mul_f32_e32 v12, v12, v12
	v_mul_f32_e32 v8, v8, v8
	v_mul_f32_e32 v13, v13, v13
	v_mul_f32_e32 v9, v9, v9
	v_mul_f32_e32 v14, v14, v14
	v_mul_f32_e32 v10, v10, v10
	v_mul_f32_e32 v15, v15, v15
	v_mul_f32_e32 v11, v11, v11
	v_mul_f32_e32 v18, v0, v0
	v_mul_f32_e32 v19, v1, v1
	v_mul_f32_e32 v20, v2, v2
	v_mul_f32_e32 v21, v3, v3
	v_cvt_pk_bf16_f32 v0, v12, v13
	v_cvt_pk_bf16_f32 v1, v14, v15
	v_cvt_pk_bf16_f32 v2, v8, v9
	v_cvt_pk_bf16_f32 v3, v10, v11
	s_mov_b64 s[4:5], -1
	v_mul_f32_e32 v4, v4, v4
	v_mul_f32_e32 v5, v5, v5
	v_mul_f32_e32 v6, v6, v6
	v_mul_f32_e32 v7, v7, v7
	global_store_dwordx4 v[16:17], v[0:3], off
	s_nop 1
	v_cvt_pk_bf16_f32 v0, v4, v5
	v_cvt_pk_bf16_f32 v1, v6, v7
	v_cvt_pk_bf16_f32 v2, v18, v19
	v_cvt_pk_bf16_f32 v3, v20, v21
	global_store_dwordx4 v[16:17], v[0:3], off offset:256
	s_cbranch_vccnz .LBB0_913
	s_andn2_b64 vcc, exec, s[10:11]
	s_cbranch_vccnz .LBB0_912
	s_barrier
	s_branch .LBB0_912
